# batched residual epilogue also for G2 layer 0 (f32 residual source, bf16 destination); far layer-loop branches chained through a second trampoline
# speedup vs baseline: 1.0112x; 1.0045x over previous
; __device__ __forceinline__ unsigned cvt_pk_bf16(float lo, float hi) { unsigned r; asm volatile("v_cvt_pk_bf16_f32 %0, %1, %2" : "=v"(r) : "v"(lo), "v"(hi)); return r; }
;     __device__ __forceinline__ void operator()(const f32x4 (&acc)[2][2][4][2], const Unit& u, int wr, int wc, int fr, int fq) const {
;         const bool lat = u.pm < NLAT / BM; const int bb = lat ? (u.pm >> 5) : 4;
;         const int row0 = (lat ? u.pm * BM : u.pm * BM - NLAT) + wr * 64 + fr, col0 = u.pn * BM + wc * 32 + 8 * fq;
;         f32x4 g[2][2];
; #pragma unroll
;         for (int bj = 0; bj < 2; ++bj)
; #pragma unroll
;             for (int n = 0; n < 2; ++n) g[bj][n] = *(const f32x4*)(gate + bb * 6144 + col0 + bj * HALF + n * 4);
; #pragma unroll
;         for (int ai = 0; ai < 2; ++ai)
; #pragma unroll
;             for (int m = 0; m < 4; ++m) {
;                 const size_t off = (size_t)(row0 + ai * HALF + m * 16) * 1024 + col0;
; #pragma unroll
;                 for (int bj = 0; bj < 2; ++bj) {
;                     f32x4 b0, b1;
;                     if (!lat) { b0 = *(const f32x4*)(baseC + off + bj * HALF); b1 = *(const f32x4*)(baseC + off + bj * HALF + 4); }
;                     else if (baseLf) { b0 = *(const f32x4*)(baseLf + off + bj * HALF); b1 = *(const f32x4*)(baseLf + off + bj * HALF + 4); }
;                     else { const u32x4 w = *(const u32x4*)(baseLb + off + bj * HALF);
;                         b0 = (f32x4){__builtin_bit_cast(float, w.x << 16), __builtin_bit_cast(float, w.x & 0xffff0000u), __builtin_bit_cast(float, w.y << 16), __builtin_bit_cast(float, w.y & 0xffff0000u)};
;                         b1 = (f32x4){__builtin_bit_cast(float, w.z << 16), __builtin_bit_cast(float, w.z & 0xffff0000u), __builtin_bit_cast(float, w.w << 16), __builtin_bit_cast(float, w.w & 0xffff0000u)}; }
;                     const f32x4 o0 = b0 + g[bj][0] * acc[ai][bj][m][0], o1 = b1 + g[bj][1] * acc[ai][bj][m][1];
;                     if (!lat) { *(f32x4*)(outC + off + bj * HALF) = o0; *(f32x4*)(outC + off + bj * HALF + 4) = o1; }
;                     else { u32x4 w; w.x = cvt_pk_bf16(o0.x, o0.y); w.y = cvt_pk_bf16(o0.z, o0.w); w.z = cvt_pk_bf16(o1.x, o1.y); w.w = cvt_pk_bf16(o1.z, o1.w); *(u32x4*)(outL + off + bj * HALF) = w; }
;                 }
;             }
;     }
.LBB0_565:
	s_cmpk_gt_i32 s42, 0x7f
	s_cselect_b64 s[48:49], -1, 0
	s_lshl_b32 s15, s42, 8
	s_lshr_b32 s14, s42, 5
	s_add_i32 s16, s15, 0xffff8000
	s_cmpk_lt_i32 s42, 0x80
	s_cselect_b64 s[12:13], -1, 0
	s_mulk_i32 s14, 0x1800
	s_and_b64 vcc, s[12:13], exec
	s_cselect_b32 s12, s14, 0x6000
	s_cselect_b32 s14, s15, s16
	s_ashr_i32 s13, s12, 31
	s_lshl_b64 s[12:13], s[12:13], 2
	v_lshl_or_b32 v162, s40, 8, v172
	s_add_u32 s12, s69, s12
	s_addc_u32 s13, s93, s13
	v_ashrrev_i32_e32 v163, 31, v162
	v_lshl_add_u64 v[44:45], v[162:163], 2, s[12:13]
	global_load_dwordx4 v[56:59], v[44:45], off offset:16
	global_load_dwordx4 v[60:63], v[44:45], off
	global_load_dwordx4 v[40:43], v[44:45], off offset:528
	s_nop 0
	global_load_dwordx4 v[44:47], v[44:45], off offset:512
	v_add_u32_e32 v164, s14, v170
	v_ashrrev_i32_e32 v165, 31, v164
	v_lshlrev_b64 v[144:145], 10, v[164:165]
	v_lshl_add_u64 v[166:167], v[144:145], 0, v[162:163]
	s_mov_b64 s[40:41], -1
	v_lshl_add_u64 v[168:169], v[166:167], 2, s[46:47]
	s_cmp_eq_u64 s[48:49], 0
	s_cbranch_scc0 .Lep2_slow
	s_cmp_eq_u64 s[52:53], 0
	s_cbranch_scc0 .Lep2_f32
	v_lshl_add_u64 v[168:169], v[166:167], 1, s[6:7]
	s_mov_b64 s[12:13], 0x8000
	s_mov_b64 s[14:15], 0x28000
	v_mov_b32_e32 v164, v168
	v_mov_b32_e32 v165, v169
	global_load_dwordx4 v[174:177], v[168:169], off
	global_load_dwordx4 v[178:181], v[168:169], off offset:256
	v_lshl_add_u64 v[168:169], v[168:169], 0, s[12:13]
	global_load_dwordx4 v[182:185], v[168:169], off
	global_load_dwordx4 v[186:189], v[168:169], off offset:256
	v_lshl_add_u64 v[168:169], v[168:169], 0, s[12:13]
	global_load_dwordx4 v[190:193], v[168:169], off
	global_load_dwordx4 v[194:197], v[168:169], off offset:256
	v_lshl_add_u64 v[168:169], v[168:169], 0, s[12:13]
	global_load_dwordx4 v[198:201], v[168:169], off
	global_load_dwordx4 v[202:205], v[168:169], off offset:256
	s_waitcnt vmcnt(7)
	v_lshlrev_b32_e32 v144, 16, v174
	v_and_b32_e32 v145, 0xffff0000, v174
	v_lshlrev_b32_e32 v146, 16, v175
	v_and_b32_e32 v147, 0xffff0000, v175
	v_lshlrev_b32_e32 v148, 16, v176
	v_and_b32_e32 v149, 0xffff0000, v176
	v_lshlrev_b32_e32 v150, 16, v177
	v_and_b32_e32 v151, 0xffff0000, v177
	v_lshl_add_u64 v[168:169], v[168:169], 0, s[14:15]
	global_load_dwordx4 v[174:177], v[168:169], off
	v_pk_fma_f32 v[140:141], v[140:141], v[60:61], v[144:145]
	v_pk_fma_f32 v[142:143], v[142:143], v[62:63], v[146:147]
	v_pk_fma_f32 v[136:137], v[136:137], v[56:57], v[148:149]
	v_pk_fma_f32 v[138:139], v[138:139], v[58:59], v[150:151]
	v_cvt_pk_bf16_f32 v140, v140, v141
	v_cvt_pk_bf16_f32 v141, v142, v143
	v_cvt_pk_bf16_f32 v142, v136, v137
	v_cvt_pk_bf16_f32 v143, v138, v139
	s_waitcnt vmcnt(7)
	v_lshlrev_b32_e32 v144, 16, v178
	v_and_b32_e32 v145, 0xffff0000, v178
	v_lshlrev_b32_e32 v146, 16, v179
	v_and_b32_e32 v147, 0xffff0000, v179
	v_lshlrev_b32_e32 v148, 16, v180
	v_and_b32_e32 v149, 0xffff0000, v180
	v_lshlrev_b32_e32 v150, 16, v181
	v_and_b32_e32 v151, 0xffff0000, v181
	global_load_dwordx4 v[178:181], v[168:169], off offset:256
	v_pk_fma_f32 v[132:133], v[132:133], v[44:45], v[144:145]
	v_pk_fma_f32 v[134:135], v[134:135], v[46:47], v[146:147]
	v_pk_fma_f32 v[128:129], v[128:129], v[40:41], v[148:149]
	v_pk_fma_f32 v[130:131], v[130:131], v[42:43], v[150:151]
	v_cvt_pk_bf16_f32 v132, v132, v133
	v_cvt_pk_bf16_f32 v133, v134, v135
	v_cvt_pk_bf16_f32 v134, v128, v129
	v_cvt_pk_bf16_f32 v135, v130, v131
	s_waitcnt vmcnt(7)
	v_lshlrev_b32_e32 v144, 16, v182
	v_and_b32_e32 v145, 0xffff0000, v182
	v_lshlrev_b32_e32 v146, 16, v183
	v_and_b32_e32 v147, 0xffff0000, v183
	v_lshlrev_b32_e32 v148, 16, v184
	v_and_b32_e32 v149, 0xffff0000, v184
	v_lshlrev_b32_e32 v150, 16, v185
	v_and_b32_e32 v151, 0xffff0000, v185
	v_lshl_add_u64 v[168:169], v[168:169], 0, s[12:13]
	global_load_dwordx4 v[182:185], v[168:169], off
	v_pk_fma_f32 v[124:125], v[124:125], v[60:61], v[144:145]
	v_pk_fma_f32 v[126:127], v[126:127], v[62:63], v[146:147]
	v_pk_fma_f32 v[120:121], v[120:121], v[56:57], v[148:149]
	v_pk_fma_f32 v[122:123], v[122:123], v[58:59], v[150:151]
	v_cvt_pk_bf16_f32 v124, v124, v125
	v_cvt_pk_bf16_f32 v125, v126, v127
	v_cvt_pk_bf16_f32 v126, v120, v121
	v_cvt_pk_bf16_f32 v127, v122, v123
	s_waitcnt vmcnt(7)
	v_lshlrev_b32_e32 v144, 16, v186
	v_and_b32_e32 v145, 0xffff0000, v186
	v_lshlrev_b32_e32 v146, 16, v187
	v_and_b32_e32 v147, 0xffff0000, v187
	v_lshlrev_b32_e32 v148, 16, v188
	v_and_b32_e32 v149, 0xffff0000, v188
	v_lshlrev_b32_e32 v150, 16, v189
	v_and_b32_e32 v151, 0xffff0000, v189
	global_load_dwordx4 v[186:189], v[168:169], off offset:256
	v_pk_fma_f32 v[116:117], v[116:117], v[44:45], v[144:145]
	v_pk_fma_f32 v[118:119], v[118:119], v[46:47], v[146:147]
	v_pk_fma_f32 v[112:113], v[112:113], v[40:41], v[148:149]
	v_pk_fma_f32 v[114:115], v[114:115], v[42:43], v[150:151]
	v_cvt_pk_bf16_f32 v116, v116, v117
	v_cvt_pk_bf16_f32 v117, v118, v119
	v_cvt_pk_bf16_f32 v118, v112, v113
	v_cvt_pk_bf16_f32 v119, v114, v115
	s_waitcnt vmcnt(7)
	v_lshlrev_b32_e32 v144, 16, v190
	v_and_b32_e32 v145, 0xffff0000, v190
	v_lshlrev_b32_e32 v146, 16, v191
	v_and_b32_e32 v147, 0xffff0000, v191
	v_lshlrev_b32_e32 v148, 16, v192
	v_and_b32_e32 v149, 0xffff0000, v192
	v_lshlrev_b32_e32 v150, 16, v193
	v_and_b32_e32 v151, 0xffff0000, v193
	v_lshl_add_u64 v[168:169], v[168:169], 0, s[12:13]
	global_load_dwordx4 v[190:193], v[168:169], off
	v_pk_fma_f32 v[108:109], v[108:109], v[60:61], v[144:145]
	v_pk_fma_f32 v[110:111], v[110:111], v[62:63], v[146:147]
	v_pk_fma_f32 v[104:105], v[104:105], v[56:57], v[148:149]
	v_pk_fma_f32 v[106:107], v[106:107], v[58:59], v[150:151]
	v_cvt_pk_bf16_f32 v108, v108, v109
	v_cvt_pk_bf16_f32 v109, v110, v111
	v_cvt_pk_bf16_f32 v110, v104, v105
	v_cvt_pk_bf16_f32 v111, v106, v107
	s_waitcnt vmcnt(7)
; __device__ __forceinline__ unsigned cvt_pk_bf16(float lo, float hi) { unsigned r; asm volatile("v_cvt_pk_bf16_f32 %0, %1, %2" : "=v"(r) : "v"(lo), "v"(hi)); return r; }
;     __device__ __forceinline__ void operator()(const f32x4 (&acc)[2][2][4][2], const Unit& u, int wr, int wc, int fr, int fq) const {
;     ...
;                 for (int bj = 0; bj < 2; ++bj) {
;                     f32x4 b0, b1;
;                     if (!lat) { b0 = *(const f32x4*)(baseC + off + bj * HALF); b1 = *(const f32x4*)(baseC + off + bj * HALF + 4); }
;                     else if (baseLf) { b0 = *(const f32x4*)(baseLf + off + bj * HALF); b1 = *(const f32x4*)(baseLf + off + bj * HALF + 4); }
;                     else { const u32x4 w = *(const u32x4*)(baseLb + off + bj * HALF);
;                         b0 = (f32x4){__builtin_bit_cast(float, w.x << 16), __builtin_bit_cast(float, w.x & 0xffff0000u), __builtin_bit_cast(float, w.y << 16), __builtin_bit_cast(float, w.y & 0xffff0000u)};
;                         b1 = (f32x4){__builtin_bit_cast(float, w.z << 16), __builtin_bit_cast(float, w.z & 0xffff0000u), __builtin_bit_cast(float, w.w << 16), __builtin_bit_cast(float, w.w & 0xffff0000u)}; }
;                     const f32x4 o0 = b0 + g[bj][0] * acc[ai][bj][m][0], o1 = b1 + g[bj][1] * acc[ai][bj][m][1];
;                     if (!lat) { *(f32x4*)(outC + off + bj * HALF) = o0; *(f32x4*)(outC + off + bj * HALF + 4) = o1; }
;                     else { u32x4 w; w.x = cvt_pk_bf16(o0.x, o0.y); w.y = cvt_pk_bf16(o0.z, o0.w); w.z = cvt_pk_bf16(o1.x, o1.y); w.w = cvt_pk_bf16(o1.z, o1.w); *(u32x4*)(outL + off + bj * HALF) = w; }
;                 }
	v_lshlrev_b32_e32 v144, 16, v194
	v_and_b32_e32 v145, 0xffff0000, v194
	v_lshlrev_b32_e32 v146, 16, v195
	v_and_b32_e32 v147, 0xffff0000, v195
	v_lshlrev_b32_e32 v148, 16, v196
	v_and_b32_e32 v149, 0xffff0000, v196
	v_lshlrev_b32_e32 v150, 16, v197
	v_and_b32_e32 v151, 0xffff0000, v197
	global_load_dwordx4 v[194:197], v[168:169], off offset:256
	v_pk_fma_f32 v[100:101], v[100:101], v[44:45], v[144:145]
	v_pk_fma_f32 v[102:103], v[102:103], v[46:47], v[146:147]
	v_pk_fma_f32 v[96:97], v[96:97], v[40:41], v[148:149]
	v_pk_fma_f32 v[98:99], v[98:99], v[42:43], v[150:151]
	v_cvt_pk_bf16_f32 v100, v100, v101
	v_cvt_pk_bf16_f32 v101, v102, v103
	v_cvt_pk_bf16_f32 v102, v96, v97
	v_cvt_pk_bf16_f32 v103, v98, v99
	s_waitcnt vmcnt(7)
	v_lshlrev_b32_e32 v144, 16, v198
	v_and_b32_e32 v145, 0xffff0000, v198
	v_lshlrev_b32_e32 v146, 16, v199
	v_and_b32_e32 v147, 0xffff0000, v199
	v_lshlrev_b32_e32 v148, 16, v200
	v_and_b32_e32 v149, 0xffff0000, v200
	v_lshlrev_b32_e32 v150, 16, v201
	v_and_b32_e32 v151, 0xffff0000, v201
	v_lshl_add_u64 v[168:169], v[168:169], 0, s[12:13]
	global_load_dwordx4 v[198:201], v[168:169], off
	v_pk_fma_f32 v[92:93], v[92:93], v[60:61], v[144:145]
	v_pk_fma_f32 v[94:95], v[94:95], v[62:63], v[146:147]
	v_pk_fma_f32 v[88:89], v[88:89], v[56:57], v[148:149]
	v_pk_fma_f32 v[90:91], v[90:91], v[58:59], v[150:151]
	v_cvt_pk_bf16_f32 v92, v92, v93
	v_cvt_pk_bf16_f32 v93, v94, v95
	v_cvt_pk_bf16_f32 v94, v88, v89
	v_cvt_pk_bf16_f32 v95, v90, v91
	s_waitcnt vmcnt(7)
	v_lshlrev_b32_e32 v144, 16, v202
	v_and_b32_e32 v145, 0xffff0000, v202
	v_lshlrev_b32_e32 v146, 16, v203
	v_and_b32_e32 v147, 0xffff0000, v203
	v_lshlrev_b32_e32 v148, 16, v204
	v_and_b32_e32 v149, 0xffff0000, v204
	v_lshlrev_b32_e32 v150, 16, v205
	v_and_b32_e32 v151, 0xffff0000, v205
	global_load_dwordx4 v[202:205], v[168:169], off offset:256
	v_pk_fma_f32 v[84:85], v[84:85], v[44:45], v[144:145]
	v_pk_fma_f32 v[86:87], v[86:87], v[46:47], v[146:147]
	v_pk_fma_f32 v[80:81], v[80:81], v[40:41], v[148:149]
	v_pk_fma_f32 v[82:83], v[82:83], v[42:43], v[150:151]
	v_cvt_pk_bf16_f32 v84, v84, v85
	v_cvt_pk_bf16_f32 v85, v86, v87
	v_cvt_pk_bf16_f32 v86, v80, v81
	v_cvt_pk_bf16_f32 v87, v82, v83
	s_waitcnt vmcnt(7)
	v_lshlrev_b32_e32 v144, 16, v174
	v_and_b32_e32 v145, 0xffff0000, v174
	v_lshlrev_b32_e32 v146, 16, v175
	v_and_b32_e32 v147, 0xffff0000, v175
	v_lshlrev_b32_e32 v148, 16, v176
	v_and_b32_e32 v149, 0xffff0000, v176
	v_lshlrev_b32_e32 v150, 16, v177
	v_and_b32_e32 v151, 0xffff0000, v177
	v_pk_fma_f32 v[76:77], v[76:77], v[60:61], v[144:145]
	v_pk_fma_f32 v[78:79], v[78:79], v[62:63], v[146:147]
	v_pk_fma_f32 v[72:73], v[72:73], v[56:57], v[148:149]
	v_pk_fma_f32 v[74:75], v[74:75], v[58:59], v[150:151]
	v_cvt_pk_bf16_f32 v76, v76, v77
	v_cvt_pk_bf16_f32 v77, v78, v79
	v_cvt_pk_bf16_f32 v78, v72, v73
	v_cvt_pk_bf16_f32 v79, v74, v75
	s_waitcnt vmcnt(6)
	v_lshlrev_b32_e32 v144, 16, v178
	v_and_b32_e32 v145, 0xffff0000, v178
	v_lshlrev_b32_e32 v146, 16, v179
	v_and_b32_e32 v147, 0xffff0000, v179
	v_lshlrev_b32_e32 v148, 16, v180
	v_and_b32_e32 v149, 0xffff0000, v180
	v_lshlrev_b32_e32 v150, 16, v181
	v_and_b32_e32 v151, 0xffff0000, v181
	v_pk_fma_f32 v[68:69], v[68:69], v[44:45], v[144:145]
	v_pk_fma_f32 v[70:71], v[70:71], v[46:47], v[146:147]
	v_pk_fma_f32 v[64:65], v[64:65], v[40:41], v[148:149]
	v_pk_fma_f32 v[66:67], v[66:67], v[42:43], v[150:151]
	v_cvt_pk_bf16_f32 v68, v68, v69
	v_cvt_pk_bf16_f32 v69, v70, v71
	v_cvt_pk_bf16_f32 v70, v64, v65
	v_cvt_pk_bf16_f32 v71, v66, v67
	s_waitcnt vmcnt(5)
	v_lshlrev_b32_e32 v144, 16, v182
	v_and_b32_e32 v145, 0xffff0000, v182
	v_lshlrev_b32_e32 v146, 16, v183
	v_and_b32_e32 v147, 0xffff0000, v183
	v_lshlrev_b32_e32 v148, 16, v184
	v_and_b32_e32 v149, 0xffff0000, v184
	v_lshlrev_b32_e32 v150, 16, v185
	v_and_b32_e32 v151, 0xffff0000, v185
	v_pk_fma_f32 v[52:53], v[52:53], v[60:61], v[144:145]
	v_pk_fma_f32 v[54:55], v[54:55], v[62:63], v[146:147]
	v_pk_fma_f32 v[48:49], v[48:49], v[56:57], v[148:149]
	v_pk_fma_f32 v[50:51], v[50:51], v[58:59], v[150:151]
	v_cvt_pk_bf16_f32 v52, v52, v53
	v_cvt_pk_bf16_f32 v53, v54, v55
	v_cvt_pk_bf16_f32 v54, v48, v49
	v_cvt_pk_bf16_f32 v55, v50, v51
	s_waitcnt vmcnt(4)
	v_lshlrev_b32_e32 v144, 16, v186
	v_and_b32_e32 v145, 0xffff0000, v186
	v_lshlrev_b32_e32 v146, 16, v187
	v_and_b32_e32 v147, 0xffff0000, v187
	v_lshlrev_b32_e32 v148, 16, v188
	v_and_b32_e32 v149, 0xffff0000, v188
	v_lshlrev_b32_e32 v150, 16, v189
	v_and_b32_e32 v151, 0xffff0000, v189
	v_pk_fma_f32 v[36:37], v[36:37], v[44:45], v[144:145]
	v_pk_fma_f32 v[38:39], v[38:39], v[46:47], v[146:147]
	v_pk_fma_f32 v[32:33], v[32:33], v[40:41], v[148:149]
	v_pk_fma_f32 v[34:35], v[34:35], v[42:43], v[150:151]
	v_cvt_pk_bf16_f32 v36, v36, v37
	v_cvt_pk_bf16_f32 v37, v38, v39
	v_cvt_pk_bf16_f32 v38, v32, v33
	v_cvt_pk_bf16_f32 v39, v34, v35
	s_waitcnt vmcnt(3)
	v_lshlrev_b32_e32 v144, 16, v190
	v_and_b32_e32 v145, 0xffff0000, v190
	v_lshlrev_b32_e32 v146, 16, v191
	v_and_b32_e32 v147, 0xffff0000, v191
	v_lshlrev_b32_e32 v148, 16, v192
	v_and_b32_e32 v149, 0xffff0000, v192
	v_lshlrev_b32_e32 v150, 16, v193
	v_and_b32_e32 v151, 0xffff0000, v193
	v_pk_fma_f32 v[28:29], v[28:29], v[60:61], v[144:145]
	v_pk_fma_f32 v[30:31], v[30:31], v[62:63], v[146:147]
	v_pk_fma_f32 v[24:25], v[24:25], v[56:57], v[148:149]
	v_pk_fma_f32 v[26:27], v[26:27], v[58:59], v[150:151]
	v_cvt_pk_bf16_f32 v28, v28, v29
	v_cvt_pk_bf16_f32 v29, v30, v31
	v_cvt_pk_bf16_f32 v30, v24, v25
	v_cvt_pk_bf16_f32 v31, v26, v27
	s_waitcnt vmcnt(2)
; __device__ __forceinline__ unsigned cvt_pk_bf16(float lo, float hi) { unsigned r; asm volatile("v_cvt_pk_bf16_f32 %0, %1, %2" : "=v"(r) : "v"(lo), "v"(hi)); return r; }
;     __device__ __forceinline__ void operator()(const f32x4 (&acc)[2][2][4][2], const Unit& u, int wr, int wc, int fr, int fq) const {
;     ...
;                 for (int bj = 0; bj < 2; ++bj) {
;                     f32x4 b0, b1;
;                     if (!lat) { b0 = *(const f32x4*)(baseC + off + bj * HALF); b1 = *(const f32x4*)(baseC + off + bj * HALF + 4); }
;                     else if (baseLf) { b0 = *(const f32x4*)(baseLf + off + bj * HALF); b1 = *(const f32x4*)(baseLf + off + bj * HALF + 4); }
;                     else { const u32x4 w = *(const u32x4*)(baseLb + off + bj * HALF);
;                         b0 = (f32x4){__builtin_bit_cast(float, w.x << 16), __builtin_bit_cast(float, w.x & 0xffff0000u), __builtin_bit_cast(float, w.y << 16), __builtin_bit_cast(float, w.y & 0xffff0000u)};
;                         b1 = (f32x4){__builtin_bit_cast(float, w.z << 16), __builtin_bit_cast(float, w.z & 0xffff0000u), __builtin_bit_cast(float, w.w << 16), __builtin_bit_cast(float, w.w & 0xffff0000u)}; }
;                     const f32x4 o0 = b0 + g[bj][0] * acc[ai][bj][m][0], o1 = b1 + g[bj][1] * acc[ai][bj][m][1];
;                     if (!lat) { *(f32x4*)(outC + off + bj * HALF) = o0; *(f32x4*)(outC + off + bj * HALF + 4) = o1; }
;                     else { u32x4 w; w.x = cvt_pk_bf16(o0.x, o0.y); w.y = cvt_pk_bf16(o0.z, o0.w); w.z = cvt_pk_bf16(o1.x, o1.y); w.w = cvt_pk_bf16(o1.z, o1.w); *(u32x4*)(outL + off + bj * HALF) = w; }
;                 }
	v_lshlrev_b32_e32 v144, 16, v194
	v_and_b32_e32 v145, 0xffff0000, v194
	v_lshlrev_b32_e32 v146, 16, v195
	v_and_b32_e32 v147, 0xffff0000, v195
	v_lshlrev_b32_e32 v148, 16, v196
	v_and_b32_e32 v149, 0xffff0000, v196
	v_lshlrev_b32_e32 v150, 16, v197
	v_and_b32_e32 v151, 0xffff0000, v197
	v_pk_fma_f32 v[20:21], v[20:21], v[44:45], v[144:145]
	v_pk_fma_f32 v[22:23], v[22:23], v[46:47], v[146:147]
	v_pk_fma_f32 v[16:17], v[16:17], v[40:41], v[148:149]
	v_pk_fma_f32 v[18:19], v[18:19], v[42:43], v[150:151]
	v_cvt_pk_bf16_f32 v20, v20, v21
	v_cvt_pk_bf16_f32 v21, v22, v23
	v_cvt_pk_bf16_f32 v22, v16, v17
	v_cvt_pk_bf16_f32 v23, v18, v19
	s_waitcnt vmcnt(1)
	v_lshlrev_b32_e32 v144, 16, v198
	v_and_b32_e32 v145, 0xffff0000, v198
	v_lshlrev_b32_e32 v146, 16, v199
	v_and_b32_e32 v147, 0xffff0000, v199
	v_lshlrev_b32_e32 v148, 16, v200
	v_and_b32_e32 v149, 0xffff0000, v200
	v_lshlrev_b32_e32 v150, 16, v201
	v_and_b32_e32 v151, 0xffff0000, v201
	v_pk_fma_f32 v[12:13], v[12:13], v[60:61], v[144:145]
	v_pk_fma_f32 v[14:15], v[14:15], v[62:63], v[146:147]
	v_pk_fma_f32 v[8:9], v[8:9], v[56:57], v[148:149]
	v_pk_fma_f32 v[10:11], v[10:11], v[58:59], v[150:151]
	v_cvt_pk_bf16_f32 v12, v12, v13
	v_cvt_pk_bf16_f32 v13, v14, v15
	v_cvt_pk_bf16_f32 v14, v8, v9
	v_cvt_pk_bf16_f32 v15, v10, v11
	s_waitcnt vmcnt(0)
	v_lshlrev_b32_e32 v144, 16, v202
	v_and_b32_e32 v145, 0xffff0000, v202
	v_lshlrev_b32_e32 v146, 16, v203
	v_and_b32_e32 v147, 0xffff0000, v203
	v_lshlrev_b32_e32 v148, 16, v204
	v_and_b32_e32 v149, 0xffff0000, v204
	v_lshlrev_b32_e32 v150, 16, v205
	v_and_b32_e32 v151, 0xffff0000, v205
	v_pk_fma_f32 v[4:5], v[4:5], v[44:45], v[144:145]
	v_pk_fma_f32 v[6:7], v[6:7], v[46:47], v[146:147]
	v_pk_fma_f32 v[0:1], v[0:1], v[40:41], v[148:149]
	v_pk_fma_f32 v[2:3], v[2:3], v[42:43], v[150:151]
	v_cvt_pk_bf16_f32 v4, v4, v5
	v_cvt_pk_bf16_f32 v5, v6, v7
	v_cvt_pk_bf16_f32 v6, v0, v1
	v_cvt_pk_bf16_f32 v7, v2, v3
	global_store_dwordx4 v[164:165], v[140:143], off
	global_store_dwordx4 v[164:165], v[132:135], off offset:256
	v_lshl_add_u64 v[164:165], v[164:165], 0, s[12:13]
	global_store_dwordx4 v[164:165], v[124:127], off
	global_store_dwordx4 v[164:165], v[116:119], off offset:256
	v_lshl_add_u64 v[164:165], v[164:165], 0, s[12:13]
	global_store_dwordx4 v[164:165], v[108:111], off
	global_store_dwordx4 v[164:165], v[100:103], off offset:256
	v_lshl_add_u64 v[164:165], v[164:165], 0, s[12:13]
	global_store_dwordx4 v[164:165], v[92:95], off
	global_store_dwordx4 v[164:165], v[84:87], off offset:256
	v_lshl_add_u64 v[164:165], v[164:165], 0, s[14:15]
	global_store_dwordx4 v[164:165], v[76:79], off
	global_store_dwordx4 v[164:165], v[68:71], off offset:256
	v_lshl_add_u64 v[164:165], v[164:165], 0, s[12:13]
	global_store_dwordx4 v[164:165], v[52:55], off
	global_store_dwordx4 v[164:165], v[36:39], off offset:256
	v_lshl_add_u64 v[164:165], v[164:165], 0, s[12:13]
	global_store_dwordx4 v[164:165], v[28:31], off
	global_store_dwordx4 v[164:165], v[20:23], off offset:256
	v_lshl_add_u64 v[164:165], v[164:165], 0, s[12:13]
	global_store_dwordx4 v[164:165], v[12:15], off
	global_store_dwordx4 v[164:165], v[4:7], off offset:256
	s_mov_b64 s[40:41], -1
	s_mov_b64 s[48:49], -1
	s_branch .Lep2_join
.Lep2_f32:
	v_lshl_add_u64 v[168:169], v[166:167], 2, s[44:45]
	v_lshl_add_u64 v[164:165], v[166:167], 1, s[6:7]
	s_mov_b64 s[12:13], 0x10000
	s_mov_b64 s[14:15], 0x50000
	global_load_dwordx4 v[174:177], v[168:169], off
	global_load_dwordx4 v[178:181], v[168:169], off offset:16
	global_load_dwordx4 v[182:185], v[168:169], off offset:512
	global_load_dwordx4 v[186:189], v[168:169], off offset:528
	v_lshl_add_u64 v[168:169], v[168:169], 0, s[12:13]
	global_load_dwordx4 v[190:193], v[168:169], off
	global_load_dwordx4 v[194:197], v[168:169], off offset:16
	global_load_dwordx4 v[198:201], v[168:169], off offset:512
	global_load_dwordx4 v[202:205], v[168:169], off offset:528
	s_waitcnt vmcnt(6)
	v_pk_fma_f32 v[140:141], v[140:141], v[60:61], v[174:175]
	v_pk_fma_f32 v[142:143], v[142:143], v[62:63], v[176:177]
	v_pk_fma_f32 v[136:137], v[136:137], v[56:57], v[178:179]
	v_pk_fma_f32 v[138:139], v[138:139], v[58:59], v[180:181]
	v_lshl_add_u64 v[168:169], v[168:169], 0, s[12:13]
	global_load_dwordx4 v[174:177], v[168:169], off
	global_load_dwordx4 v[178:181], v[168:169], off offset:16
	v_cvt_pk_bf16_f32 v140, v140, v141
	v_cvt_pk_bf16_f32 v141, v142, v143
	v_cvt_pk_bf16_f32 v142, v136, v137
	v_cvt_pk_bf16_f32 v143, v138, v139
	s_waitcnt vmcnt(6)
	v_pk_fma_f32 v[132:133], v[132:133], v[44:45], v[182:183]
	v_pk_fma_f32 v[134:135], v[134:135], v[46:47], v[184:185]
	v_pk_fma_f32 v[128:129], v[128:129], v[40:41], v[186:187]
	v_pk_fma_f32 v[130:131], v[130:131], v[42:43], v[188:189]
	global_load_dwordx4 v[182:185], v[168:169], off offset:512
	global_load_dwordx4 v[186:189], v[168:169], off offset:528
	v_cvt_pk_bf16_f32 v132, v132, v133
	v_cvt_pk_bf16_f32 v133, v134, v135
	v_cvt_pk_bf16_f32 v134, v128, v129
	v_cvt_pk_bf16_f32 v135, v130, v131
	s_waitcnt vmcnt(6)
	v_pk_fma_f32 v[124:125], v[124:125], v[60:61], v[190:191]
	v_pk_fma_f32 v[126:127], v[126:127], v[62:63], v[192:193]
	v_pk_fma_f32 v[120:121], v[120:121], v[56:57], v[194:195]
	v_pk_fma_f32 v[122:123], v[122:123], v[58:59], v[196:197]
	v_lshl_add_u64 v[168:169], v[168:169], 0, s[12:13]
	global_load_dwordx4 v[190:193], v[168:169], off
	global_load_dwordx4 v[194:197], v[168:169], off offset:16
	v_cvt_pk_bf16_f32 v124, v124, v125
	v_cvt_pk_bf16_f32 v125, v126, v127
	v_cvt_pk_bf16_f32 v126, v120, v121
	v_cvt_pk_bf16_f32 v127, v122, v123
	s_waitcnt vmcnt(6)
; __device__ __forceinline__ unsigned cvt_pk_bf16(float lo, float hi) { unsigned r; asm volatile("v_cvt_pk_bf16_f32 %0, %1, %2" : "=v"(r) : "v"(lo), "v"(hi)); return r; }
;     __device__ __forceinline__ void operator()(const f32x4 (&acc)[2][2][4][2], const Unit& u, int wr, int wc, int fr, int fq) const {
;     ...
;                 for (int bj = 0; bj < 2; ++bj) {
;                     f32x4 b0, b1;
;                     if (!lat) { b0 = *(const f32x4*)(baseC + off + bj * HALF); b1 = *(const f32x4*)(baseC + off + bj * HALF + 4); }
;                     else if (baseLf) { b0 = *(const f32x4*)(baseLf + off + bj * HALF); b1 = *(const f32x4*)(baseLf + off + bj * HALF + 4); }
;                     else { const u32x4 w = *(const u32x4*)(baseLb + off + bj * HALF);
;                         b0 = (f32x4){__builtin_bit_cast(float, w.x << 16), __builtin_bit_cast(float, w.x & 0xffff0000u), __builtin_bit_cast(float, w.y << 16), __builtin_bit_cast(float, w.y & 0xffff0000u)};
;                         b1 = (f32x4){__builtin_bit_cast(float, w.z << 16), __builtin_bit_cast(float, w.z & 0xffff0000u), __builtin_bit_cast(float, w.w << 16), __builtin_bit_cast(float, w.w & 0xffff0000u)}; }
;                     const f32x4 o0 = b0 + g[bj][0] * acc[ai][bj][m][0], o1 = b1 + g[bj][1] * acc[ai][bj][m][1];
;                     if (!lat) { *(f32x4*)(outC + off + bj * HALF) = o0; *(f32x4*)(outC + off + bj * HALF + 4) = o1; }
;                     else { u32x4 w; w.x = cvt_pk_bf16(o0.x, o0.y); w.y = cvt_pk_bf16(o0.z, o0.w); w.z = cvt_pk_bf16(o1.x, o1.y); w.w = cvt_pk_bf16(o1.z, o1.w); *(u32x4*)(outL + off + bj * HALF) = w; }
;                 }
	v_pk_fma_f32 v[116:117], v[116:117], v[44:45], v[198:199]
	v_pk_fma_f32 v[118:119], v[118:119], v[46:47], v[200:201]
	v_pk_fma_f32 v[112:113], v[112:113], v[40:41], v[202:203]
	v_pk_fma_f32 v[114:115], v[114:115], v[42:43], v[204:205]
	global_load_dwordx4 v[198:201], v[168:169], off offset:512
	global_load_dwordx4 v[202:205], v[168:169], off offset:528
	v_cvt_pk_bf16_f32 v116, v116, v117
	v_cvt_pk_bf16_f32 v117, v118, v119
	v_cvt_pk_bf16_f32 v118, v112, v113
	v_cvt_pk_bf16_f32 v119, v114, v115
	s_waitcnt vmcnt(6)
	v_pk_fma_f32 v[108:109], v[108:109], v[60:61], v[174:175]
	v_pk_fma_f32 v[110:111], v[110:111], v[62:63], v[176:177]
	v_pk_fma_f32 v[104:105], v[104:105], v[56:57], v[178:179]
	v_pk_fma_f32 v[106:107], v[106:107], v[58:59], v[180:181]
	v_lshl_add_u64 v[168:169], v[168:169], 0, s[14:15]
	global_load_dwordx4 v[174:177], v[168:169], off
	global_load_dwordx4 v[178:181], v[168:169], off offset:16
	v_cvt_pk_bf16_f32 v108, v108, v109
	v_cvt_pk_bf16_f32 v109, v110, v111
	v_cvt_pk_bf16_f32 v110, v104, v105
	v_cvt_pk_bf16_f32 v111, v106, v107
	s_waitcnt vmcnt(6)
	v_pk_fma_f32 v[100:101], v[100:101], v[44:45], v[182:183]
	v_pk_fma_f32 v[102:103], v[102:103], v[46:47], v[184:185]
	v_pk_fma_f32 v[96:97], v[96:97], v[40:41], v[186:187]
	v_pk_fma_f32 v[98:99], v[98:99], v[42:43], v[188:189]
	global_load_dwordx4 v[182:185], v[168:169], off offset:512
	global_load_dwordx4 v[186:189], v[168:169], off offset:528
	v_cvt_pk_bf16_f32 v100, v100, v101
	v_cvt_pk_bf16_f32 v101, v102, v103
	v_cvt_pk_bf16_f32 v102, v96, v97
	v_cvt_pk_bf16_f32 v103, v98, v99
	s_waitcnt vmcnt(6)
	v_pk_fma_f32 v[92:93], v[92:93], v[60:61], v[190:191]
	v_pk_fma_f32 v[94:95], v[94:95], v[62:63], v[192:193]
	v_pk_fma_f32 v[88:89], v[88:89], v[56:57], v[194:195]
	v_pk_fma_f32 v[90:91], v[90:91], v[58:59], v[196:197]
	v_lshl_add_u64 v[168:169], v[168:169], 0, s[12:13]
	global_load_dwordx4 v[190:193], v[168:169], off
	global_load_dwordx4 v[194:197], v[168:169], off offset:16
	v_cvt_pk_bf16_f32 v92, v92, v93
	v_cvt_pk_bf16_f32 v93, v94, v95
	v_cvt_pk_bf16_f32 v94, v88, v89
	v_cvt_pk_bf16_f32 v95, v90, v91
	s_waitcnt vmcnt(6)
	v_pk_fma_f32 v[84:85], v[84:85], v[44:45], v[198:199]
	v_pk_fma_f32 v[86:87], v[86:87], v[46:47], v[200:201]
	v_pk_fma_f32 v[80:81], v[80:81], v[40:41], v[202:203]
	v_pk_fma_f32 v[82:83], v[82:83], v[42:43], v[204:205]
	global_load_dwordx4 v[198:201], v[168:169], off offset:512
	global_load_dwordx4 v[202:205], v[168:169], off offset:528
	v_cvt_pk_bf16_f32 v84, v84, v85
	v_cvt_pk_bf16_f32 v85, v86, v87
	v_cvt_pk_bf16_f32 v86, v80, v81
	v_cvt_pk_bf16_f32 v87, v82, v83
	s_waitcnt vmcnt(6)
	v_pk_fma_f32 v[76:77], v[76:77], v[60:61], v[174:175]
	v_pk_fma_f32 v[78:79], v[78:79], v[62:63], v[176:177]
	v_pk_fma_f32 v[72:73], v[72:73], v[56:57], v[178:179]
	v_pk_fma_f32 v[74:75], v[74:75], v[58:59], v[180:181]
	v_lshl_add_u64 v[168:169], v[168:169], 0, s[12:13]
	global_load_dwordx4 v[174:177], v[168:169], off
	global_load_dwordx4 v[178:181], v[168:169], off offset:16
	v_cvt_pk_bf16_f32 v76, v76, v77
	v_cvt_pk_bf16_f32 v77, v78, v79
	v_cvt_pk_bf16_f32 v78, v72, v73
	v_cvt_pk_bf16_f32 v79, v74, v75
	s_waitcnt vmcnt(6)
	v_pk_fma_f32 v[68:69], v[68:69], v[44:45], v[182:183]
	v_pk_fma_f32 v[70:71], v[70:71], v[46:47], v[184:185]
	v_pk_fma_f32 v[64:65], v[64:65], v[40:41], v[186:187]
	v_pk_fma_f32 v[66:67], v[66:67], v[42:43], v[188:189]
	global_load_dwordx4 v[182:185], v[168:169], off offset:512
	global_load_dwordx4 v[186:189], v[168:169], off offset:528
	v_cvt_pk_bf16_f32 v68, v68, v69
	v_cvt_pk_bf16_f32 v69, v70, v71
	v_cvt_pk_bf16_f32 v70, v64, v65
	v_cvt_pk_bf16_f32 v71, v66, v67
	s_waitcnt vmcnt(6)
; __device__ __forceinline__ unsigned cvt_pk_bf16(float lo, float hi) { unsigned r; asm volatile("v_cvt_pk_bf16_f32 %0, %1, %2" : "=v"(r) : "v"(lo), "v"(hi)); return r; }
;     __device__ __forceinline__ void operator()(const f32x4 (&acc)[2][2][4][2], const Unit& u, int wr, int wc, int fr, int fq) const {
;     ...
;                 for (int bj = 0; bj < 2; ++bj) {
;                     f32x4 b0, b1;
;                     if (!lat) { b0 = *(const f32x4*)(baseC + off + bj * HALF); b1 = *(const f32x4*)(baseC + off + bj * HALF + 4); }
;                     else if (baseLf) { b0 = *(const f32x4*)(baseLf + off + bj * HALF); b1 = *(const f32x4*)(baseLf + off + bj * HALF + 4); }
;                     else { const u32x4 w = *(const u32x4*)(baseLb + off + bj * HALF);
;                         b0 = (f32x4){__builtin_bit_cast(float, w.x << 16), __builtin_bit_cast(float, w.x & 0xffff0000u), __builtin_bit_cast(float, w.y << 16), __builtin_bit_cast(float, w.y & 0xffff0000u)};
;                         b1 = (f32x4){__builtin_bit_cast(float, w.z << 16), __builtin_bit_cast(float, w.z & 0xffff0000u), __builtin_bit_cast(float, w.w << 16), __builtin_bit_cast(float, w.w & 0xffff0000u)}; }
;                     const f32x4 o0 = b0 + g[bj][0] * acc[ai][bj][m][0], o1 = b1 + g[bj][1] * acc[ai][bj][m][1];
;                     if (!lat) { *(f32x4*)(outC + off + bj * HALF) = o0; *(f32x4*)(outC + off + bj * HALF + 4) = o1; }
;                     else { u32x4 w; w.x = cvt_pk_bf16(o0.x, o0.y); w.y = cvt_pk_bf16(o0.z, o0.w); w.z = cvt_pk_bf16(o1.x, o1.y); w.w = cvt_pk_bf16(o1.z, o1.w); *(u32x4*)(outL + off + bj * HALF) = w; }
;                 }
	v_pk_fma_f32 v[52:53], v[52:53], v[60:61], v[190:191]
	v_pk_fma_f32 v[54:55], v[54:55], v[62:63], v[192:193]
	v_pk_fma_f32 v[48:49], v[48:49], v[56:57], v[194:195]
	v_pk_fma_f32 v[50:51], v[50:51], v[58:59], v[196:197]
	v_lshl_add_u64 v[168:169], v[168:169], 0, s[12:13]
	global_load_dwordx4 v[190:193], v[168:169], off
	global_load_dwordx4 v[194:197], v[168:169], off offset:16
	v_cvt_pk_bf16_f32 v52, v52, v53
	v_cvt_pk_bf16_f32 v53, v54, v55
	v_cvt_pk_bf16_f32 v54, v48, v49
	v_cvt_pk_bf16_f32 v55, v50, v51
	s_waitcnt vmcnt(6)
	v_pk_fma_f32 v[36:37], v[36:37], v[44:45], v[198:199]
	v_pk_fma_f32 v[38:39], v[38:39], v[46:47], v[200:201]
	v_pk_fma_f32 v[32:33], v[32:33], v[40:41], v[202:203]
	v_pk_fma_f32 v[34:35], v[34:35], v[42:43], v[204:205]
	global_load_dwordx4 v[198:201], v[168:169], off offset:512
	global_load_dwordx4 v[202:205], v[168:169], off offset:528
	v_cvt_pk_bf16_f32 v36, v36, v37
	v_cvt_pk_bf16_f32 v37, v38, v39
	v_cvt_pk_bf16_f32 v38, v32, v33
	v_cvt_pk_bf16_f32 v39, v34, v35
	s_waitcnt vmcnt(6)
	v_pk_fma_f32 v[28:29], v[28:29], v[60:61], v[174:175]
	v_pk_fma_f32 v[30:31], v[30:31], v[62:63], v[176:177]
	v_pk_fma_f32 v[24:25], v[24:25], v[56:57], v[178:179]
	v_pk_fma_f32 v[26:27], v[26:27], v[58:59], v[180:181]
	v_cvt_pk_bf16_f32 v28, v28, v29
	v_cvt_pk_bf16_f32 v29, v30, v31
	v_cvt_pk_bf16_f32 v30, v24, v25
	v_cvt_pk_bf16_f32 v31, v26, v27
	s_waitcnt vmcnt(4)
	v_pk_fma_f32 v[20:21], v[20:21], v[44:45], v[182:183]
	v_pk_fma_f32 v[22:23], v[22:23], v[46:47], v[184:185]
	v_pk_fma_f32 v[16:17], v[16:17], v[40:41], v[186:187]
	v_pk_fma_f32 v[18:19], v[18:19], v[42:43], v[188:189]
	v_cvt_pk_bf16_f32 v20, v20, v21
	v_cvt_pk_bf16_f32 v21, v22, v23
	v_cvt_pk_bf16_f32 v22, v16, v17
	v_cvt_pk_bf16_f32 v23, v18, v19
	s_waitcnt vmcnt(2)
	v_pk_fma_f32 v[12:13], v[12:13], v[60:61], v[190:191]
	v_pk_fma_f32 v[14:15], v[14:15], v[62:63], v[192:193]
	v_pk_fma_f32 v[8:9], v[8:9], v[56:57], v[194:195]
	v_pk_fma_f32 v[10:11], v[10:11], v[58:59], v[196:197]
	v_cvt_pk_bf16_f32 v12, v12, v13
	v_cvt_pk_bf16_f32 v13, v14, v15
	v_cvt_pk_bf16_f32 v14, v8, v9
	v_cvt_pk_bf16_f32 v15, v10, v11
	s_waitcnt vmcnt(0)
	v_pk_fma_f32 v[4:5], v[4:5], v[44:45], v[198:199]
	v_pk_fma_f32 v[6:7], v[6:7], v[46:47], v[200:201]
	v_pk_fma_f32 v[0:1], v[0:1], v[40:41], v[202:203]
	v_pk_fma_f32 v[2:3], v[2:3], v[42:43], v[204:205]
	v_cvt_pk_bf16_f32 v4, v4, v5
	v_cvt_pk_bf16_f32 v5, v6, v7
	v_cvt_pk_bf16_f32 v6, v0, v1
	v_cvt_pk_bf16_f32 v7, v2, v3
	s_mov_b64 s[12:13], 0x8000
	s_mov_b64 s[14:15], 0x28000
	global_store_dwordx4 v[164:165], v[140:143], off
	global_store_dwordx4 v[164:165], v[132:135], off offset:256
	v_lshl_add_u64 v[164:165], v[164:165], 0, s[12:13]
	global_store_dwordx4 v[164:165], v[124:127], off
	global_store_dwordx4 v[164:165], v[116:119], off offset:256
	v_lshl_add_u64 v[164:165], v[164:165], 0, s[12:13]
	global_store_dwordx4 v[164:165], v[108:111], off
	global_store_dwordx4 v[164:165], v[100:103], off offset:256
	v_lshl_add_u64 v[164:165], v[164:165], 0, s[12:13]
	global_store_dwordx4 v[164:165], v[92:95], off
	global_store_dwordx4 v[164:165], v[84:87], off offset:256
	v_lshl_add_u64 v[164:165], v[164:165], 0, s[14:15]
	global_store_dwordx4 v[164:165], v[76:79], off
	global_store_dwordx4 v[164:165], v[68:71], off offset:256
	v_lshl_add_u64 v[164:165], v[164:165], 0, s[12:13]
	global_store_dwordx4 v[164:165], v[52:55], off
	global_store_dwordx4 v[164:165], v[36:39], off offset:256
	v_lshl_add_u64 v[164:165], v[164:165], 0, s[12:13]
	global_store_dwordx4 v[164:165], v[28:31], off
	global_store_dwordx4 v[164:165], v[20:23], off offset:256
	v_lshl_add_u64 v[164:165], v[164:165], 0, s[12:13]
	global_store_dwordx4 v[164:165], v[12:15], off
	global_store_dwordx4 v[164:165], v[4:7], off offset:256
	s_mov_b64 s[40:41], -1
	s_mov_b64 s[48:49], -1
	s_branch .Lep2_join
.Lep2_tramp117:
	s_branch .Lat_tramp117
.Lep2_slow:
	s_cbranch_vccnz .LBB0_567
	global_load_dwordx4 v[144:147], v[168:169], off offset:16
	global_load_dwordx4 v[148:151], v[168:169], off
	s_mov_b64 s[40:41], 0
